# ctx_fin loops: rolling prefetch (group j+2 loads issued when group j registers free), ctx_fin<4> site rewritten too
# speedup vs baseline: 1.0517x; 1.0022x over previous
.LBB0_472:
	s_waitcnt lgkmcnt(0)
	v_lshl_add_u64 v[52:53], v[32:33], 0, v[8:9]
	v_lshl_add_u64 v[56:57], v[34:35], 0, v[8:9]
	v_add_u32_e32 v64, 0x4000, v6
	v_ashrrev_i32_e32 v65, 31, v64
	v_lshlrev_b64 v[58:59], 11, v[64:65]
	v_lshl_add_u64 v[58:59], v[28:29], 0, v[58:59]
	s_mov_b32 s85, 0
	s_mov_b32 s84, 0x400000
	v_lshl_add_u64 v[54:55], v[52:53], 0, s[84:85]
	s_mov_b32 s84, 0xda00000
	v_lshl_add_u64 v[88:89], v[52:53], 0, s[84:85]
	s_add_u32 s84, s84, 0x400000
	v_lshl_add_u64 v[90:91], v[52:53], 0, s[84:85]
	s_add_u32 s84, s84, 0x400000
	v_lshl_add_u64 v[92:93], v[52:53], 0, s[84:85]
	s_add_u32 s84, s84, 0x400000
	v_lshl_add_u64 v[94:95], v[52:53], 0, s[84:85]
	s_add_u32 s84, s84, 0x400000
	v_lshl_add_u64 v[96:97], v[52:53], 0, s[84:85]
	s_add_u32 s84, s84, 0x400000
	v_lshl_add_u64 v[98:99], v[52:53], 0, s[84:85]
	s_add_u32 s84, s84, 0x400000
	v_lshl_add_u64 v[100:101], v[52:53], 0, s[84:85]
	s_add_u32 s84, s84, 0x400000
	v_lshl_add_u64 v[102:103], v[52:53], 0, s[84:85]
	s_add_u32 s84, s84, 0x400000
	v_lshl_add_u64 v[104:105], v[52:53], 0, s[84:85]
	s_add_u32 s84, s84, 0x400000
	v_lshl_add_u64 v[106:107], v[52:53], 0, s[84:85]
	s_add_u32 s84, s84, 0x400000
	v_lshl_add_u64 v[108:109], v[52:53], 0, s[84:85]
	global_load_dwordx4 v[42:45], v[88:89], off
	global_load_dwordx4 v[46:49], v[90:91], off
	global_load_dwordx4 v[110:113], v[92:93], off
	global_load_dwordx4 v[114:117], v[94:95], off
	global_load_dwordx4 v[118:121], v[96:97], off
	global_load_dwordx4 v[122:125], v[98:99], off
	global_load_dwordx4 v[126:129], v[100:101], off
	global_load_dwordx4 v[130:133], v[102:103], off
	global_load_dwordx4 v[134:137], v[104:105], off
	global_load_dwordx4 v[138:141], v[106:107], off
	global_load_dwordx4 v[142:145], v[108:109], off
	global_load_dwordx4 v[148:151], v[56:57], off
	global_load_dwordx4 v[152:155], v[10:11], off
	global_load_dwordx4 v[156:159], v[12:13], off
	global_load_dwordx4 v[160:163], v[14:15], off
	global_load_dwordx4 v[164:167], v[88:89], off offset:1024
	global_load_dwordx4 v[168:171], v[90:91], off offset:1024
	global_load_dwordx4 v[172:175], v[92:93], off offset:1024
	global_load_dwordx4 v[176:179], v[94:95], off offset:1024
	global_load_dwordx4 v[180:183], v[96:97], off offset:1024
	global_load_dwordx4 v[184:187], v[98:99], off offset:1024
	global_load_dwordx4 v[188:191], v[100:101], off offset:1024
	global_load_dwordx4 v[192:195], v[102:103], off offset:1024
	global_load_dwordx4 v[196:199], v[104:105], off offset:1024
	global_load_dwordx4 v[200:203], v[106:107], off offset:1024
	global_load_dwordx4 v[204:207], v[108:109], off offset:1024
	global_load_dwordx4 v[208:211], v[56:57], off offset:1024
	global_load_dwordx4 v[212:215], v[10:11], off offset:1024
	global_load_dwordx4 v[216:219], v[12:13], off offset:1024
	global_load_dwordx4 v[220:223], v[14:15], off offset:1024
	s_waitcnt vmcnt(15)
	v_pk_add_f32 v[62:63], v[44:45], 0 op_sel_hi:[1,0]
	v_pk_add_f32 v[60:61], v[42:43], 0 op_sel_hi:[1,0]
	v_pk_add_f32 v[62:63], v[62:63], v[48:49]
	v_pk_add_f32 v[60:61], v[60:61], v[46:47]
	v_pk_add_f32 v[62:63], v[62:63], v[112:113]
	v_pk_add_f32 v[60:61], v[60:61], v[110:111]
	v_pk_add_f32 v[62:63], v[62:63], v[116:117]
	v_pk_add_f32 v[60:61], v[60:61], v[114:115]
	v_pk_add_f32 v[62:63], v[62:63], v[120:121]
	v_pk_add_f32 v[60:61], v[60:61], v[118:119]
	v_pk_add_f32 v[62:63], v[62:63], v[124:125]
	v_pk_add_f32 v[60:61], v[60:61], v[122:123]
	v_pk_add_f32 v[62:63], v[62:63], v[128:129]
	v_pk_add_f32 v[60:61], v[60:61], v[126:127]
	v_pk_add_f32 v[62:63], v[62:63], v[132:133]
	v_pk_add_f32 v[60:61], v[60:61], v[130:131]
	v_pk_add_f32 v[62:63], v[62:63], v[136:137]
	v_pk_add_f32 v[60:61], v[60:61], v[134:135]
	v_pk_add_f32 v[62:63], v[62:63], v[140:141]
	v_pk_add_f32 v[60:61], v[60:61], v[138:139]
	v_pk_add_f32 v[62:63], v[62:63], v[144:145]
	v_pk_add_f32 v[60:61], v[60:61], v[142:143]
	v_pk_mul_f32 v[154:155], v[154:155], 0.5 op_sel_hi:[1,0]
	v_pk_mul_f32 v[152:153], v[152:153], 0.5 op_sel_hi:[1,0]
	v_pk_fma_f32 v[82:83], v[62:63], v[154:155], v[150:151]
	v_pk_fma_f32 v[80:81], v[60:61], v[152:153], v[148:149]
	v_mul_f32_e32 v66, v83, v83
	v_mul_f32_e32 v7, v81, v81
	global_store_dwordx4 v[54:55], v[80:83], off
	v_fmac_f32_e32 v7, v80, v80
	v_fmac_f32_e32 v66, v82, v82
	v_add_f32_e32 v7, v7, v66
	v_pk_add_f32 v[162:163], v[162:163], 1.0 op_sel_hi:[1,0]
	v_pk_add_f32 v[160:161], v[160:161], 1.0 op_sel_hi:[1,0]
	v_pk_mul_f32 v[158:159], v[158:159], v[162:163]
	v_pk_mul_f32 v[156:157], v[156:157], v[160:161]
	v_pk_mul_f32 v[86:87], v[82:83], v[158:159]
	v_pk_mul_f32 v[84:85], v[80:81], v[156:157]
	s_nop 0
	v_cvt_pk_bf16_f32 v84, v84, v85
	v_cvt_pk_bf16_f32 v85, v86, v87
	global_store_dwordx2 v[58:59], v[84:85], off
	global_load_dwordx4 v[42:45], v[88:89], off offset:2048
	global_load_dwordx4 v[46:49], v[90:91], off offset:2048
	global_load_dwordx4 v[110:113], v[92:93], off offset:2048
	global_load_dwordx4 v[114:117], v[94:95], off offset:2048
	global_load_dwordx4 v[118:121], v[96:97], off offset:2048
	global_load_dwordx4 v[122:125], v[98:99], off offset:2048
	global_load_dwordx4 v[126:129], v[100:101], off offset:2048
	global_load_dwordx4 v[130:133], v[102:103], off offset:2048
	global_load_dwordx4 v[134:137], v[104:105], off offset:2048
	global_load_dwordx4 v[138:141], v[106:107], off offset:2048
	global_load_dwordx4 v[142:145], v[108:109], off offset:2048
	global_load_dwordx4 v[148:151], v[56:57], off offset:2048
	global_load_dwordx4 v[152:155], v[10:11], off offset:2048
	global_load_dwordx4 v[156:159], v[12:13], off offset:2048
	global_load_dwordx4 v[160:163], v[14:15], off offset:2048
	s_waitcnt vmcnt(17)
	v_pk_add_f32 v[62:63], v[166:167], 0 op_sel_hi:[1,0]
	v_pk_add_f32 v[60:61], v[164:165], 0 op_sel_hi:[1,0]
	v_pk_add_f32 v[62:63], v[62:63], v[170:171]
	v_pk_add_f32 v[60:61], v[60:61], v[168:169]
	v_pk_add_f32 v[62:63], v[62:63], v[174:175]
	v_pk_add_f32 v[60:61], v[60:61], v[172:173]
	v_pk_add_f32 v[62:63], v[62:63], v[178:179]
	v_pk_add_f32 v[60:61], v[60:61], v[176:177]
	v_pk_add_f32 v[62:63], v[62:63], v[182:183]
	v_pk_add_f32 v[60:61], v[60:61], v[180:181]
	v_pk_add_f32 v[62:63], v[62:63], v[186:187]
	v_pk_add_f32 v[60:61], v[60:61], v[184:185]
	v_pk_add_f32 v[62:63], v[62:63], v[190:191]
	v_pk_add_f32 v[60:61], v[60:61], v[188:189]
	v_pk_add_f32 v[62:63], v[62:63], v[194:195]
	v_pk_add_f32 v[60:61], v[60:61], v[192:193]
	v_pk_add_f32 v[62:63], v[62:63], v[198:199]
	v_pk_add_f32 v[60:61], v[60:61], v[196:197]
	v_pk_add_f32 v[62:63], v[62:63], v[202:203]
	v_pk_add_f32 v[60:61], v[60:61], v[200:201]
	v_pk_add_f32 v[62:63], v[62:63], v[206:207]
	v_pk_add_f32 v[60:61], v[60:61], v[204:205]
	v_pk_mul_f32 v[214:215], v[214:215], 0.5 op_sel_hi:[1,0]
	v_pk_mul_f32 v[212:213], v[212:213], 0.5 op_sel_hi:[1,0]
	v_pk_fma_f32 v[82:83], v[62:63], v[214:215], v[210:211]
	v_pk_fma_f32 v[80:81], v[60:61], v[212:213], v[208:209]
	v_mul_f32_e32 v67, v83, v83
	v_mul_f32_e32 v66, v81, v81
	v_fmac_f32_e32 v66, v80, v80
	v_fmac_f32_e32 v67, v82, v82
	global_store_dwordx4 v[54:55], v[80:83], off offset:1024
	v_add_f32_e32 v66, v66, v67
	v_add_f32_e32 v7, v7, v66
	v_pk_add_f32 v[222:223], v[222:223], 1.0 op_sel_hi:[1,0]
	v_pk_add_f32 v[220:221], v[220:221], 1.0 op_sel_hi:[1,0]
	v_pk_mul_f32 v[218:219], v[218:219], v[222:223]
	v_pk_mul_f32 v[216:217], v[216:217], v[220:221]
	v_pk_mul_f32 v[86:87], v[82:83], v[218:219]
	v_pk_mul_f32 v[84:85], v[80:81], v[216:217]
	s_nop 0
	v_cvt_pk_bf16_f32 v84, v84, v85
	v_cvt_pk_bf16_f32 v85, v86, v87
	global_store_dwordx2 v[58:59], v[84:85], off offset:512
	global_load_dwordx4 v[164:167], v[88:89], off offset:3072
	global_load_dwordx4 v[168:171], v[90:91], off offset:3072
	global_load_dwordx4 v[172:175], v[92:93], off offset:3072
	global_load_dwordx4 v[176:179], v[94:95], off offset:3072
	global_load_dwordx4 v[180:183], v[96:97], off offset:3072
	global_load_dwordx4 v[184:187], v[98:99], off offset:3072
	global_load_dwordx4 v[188:191], v[100:101], off offset:3072
	global_load_dwordx4 v[192:195], v[102:103], off offset:3072
	global_load_dwordx4 v[196:199], v[104:105], off offset:3072
	global_load_dwordx4 v[200:203], v[106:107], off offset:3072
	global_load_dwordx4 v[204:207], v[108:109], off offset:3072
	global_load_dwordx4 v[208:211], v[56:57], off offset:3072
	global_load_dwordx4 v[212:215], v[10:11], off offset:3072
	global_load_dwordx4 v[216:219], v[12:13], off offset:3072
	global_load_dwordx4 v[220:223], v[14:15], off offset:3072
	s_waitcnt vmcnt(17)
	v_pk_add_f32 v[62:63], v[44:45], 0 op_sel_hi:[1,0]
	v_pk_add_f32 v[60:61], v[42:43], 0 op_sel_hi:[1,0]
	v_pk_add_f32 v[62:63], v[62:63], v[48:49]
	v_pk_add_f32 v[60:61], v[60:61], v[46:47]
	v_pk_add_f32 v[62:63], v[62:63], v[112:113]
	v_pk_add_f32 v[60:61], v[60:61], v[110:111]
	v_pk_add_f32 v[62:63], v[62:63], v[116:117]
	v_pk_add_f32 v[60:61], v[60:61], v[114:115]
	v_pk_add_f32 v[62:63], v[62:63], v[120:121]
	v_pk_add_f32 v[60:61], v[60:61], v[118:119]
	v_pk_add_f32 v[62:63], v[62:63], v[124:125]
	v_pk_add_f32 v[60:61], v[60:61], v[122:123]
	v_pk_add_f32 v[62:63], v[62:63], v[128:129]
	v_pk_add_f32 v[60:61], v[60:61], v[126:127]
	v_pk_add_f32 v[62:63], v[62:63], v[132:133]
	v_pk_add_f32 v[60:61], v[60:61], v[130:131]
	v_pk_add_f32 v[62:63], v[62:63], v[136:137]
	v_pk_add_f32 v[60:61], v[60:61], v[134:135]
	v_pk_add_f32 v[62:63], v[62:63], v[140:141]
	v_pk_add_f32 v[60:61], v[60:61], v[138:139]
	v_pk_add_f32 v[62:63], v[62:63], v[144:145]
	v_pk_add_f32 v[60:61], v[60:61], v[142:143]
	v_pk_mul_f32 v[154:155], v[154:155], 0.5 op_sel_hi:[1,0]
	v_pk_mul_f32 v[152:153], v[152:153], 0.5 op_sel_hi:[1,0]
	v_pk_fma_f32 v[82:83], v[62:63], v[154:155], v[150:151]
	v_pk_fma_f32 v[80:81], v[60:61], v[152:153], v[148:149]
	v_mul_f32_e32 v67, v83, v83
	v_mul_f32_e32 v66, v81, v81
	v_fmac_f32_e32 v66, v80, v80
	v_fmac_f32_e32 v67, v82, v82
	global_store_dwordx4 v[54:55], v[80:83], off offset:2048
	v_add_f32_e32 v66, v66, v67
	v_add_f32_e32 v7, v7, v66
	v_pk_add_f32 v[162:163], v[162:163], 1.0 op_sel_hi:[1,0]
	v_pk_add_f32 v[160:161], v[160:161], 1.0 op_sel_hi:[1,0]
	v_pk_mul_f32 v[158:159], v[158:159], v[162:163]
	v_pk_mul_f32 v[156:157], v[156:157], v[160:161]
	v_pk_mul_f32 v[86:87], v[82:83], v[158:159]
	v_pk_mul_f32 v[84:85], v[80:81], v[156:157]
	s_nop 0
	v_cvt_pk_bf16_f32 v84, v84, v85
	v_cvt_pk_bf16_f32 v85, v86, v87
	global_store_dwordx2 v[58:59], v[84:85], off offset:1024
	s_waitcnt vmcnt(2)
	v_pk_add_f32 v[62:63], v[166:167], 0 op_sel_hi:[1,0]
	v_pk_add_f32 v[60:61], v[164:165], 0 op_sel_hi:[1,0]
	v_pk_add_f32 v[62:63], v[62:63], v[170:171]
	v_pk_add_f32 v[60:61], v[60:61], v[168:169]
	v_pk_add_f32 v[62:63], v[62:63], v[174:175]
	v_pk_add_f32 v[60:61], v[60:61], v[172:173]
	v_pk_add_f32 v[62:63], v[62:63], v[178:179]
	v_pk_add_f32 v[60:61], v[60:61], v[176:177]
	v_pk_add_f32 v[62:63], v[62:63], v[182:183]
	v_pk_add_f32 v[60:61], v[60:61], v[180:181]
	v_pk_add_f32 v[62:63], v[62:63], v[186:187]
	v_pk_add_f32 v[60:61], v[60:61], v[184:185]
	v_pk_add_f32 v[62:63], v[62:63], v[190:191]
	v_pk_add_f32 v[60:61], v[60:61], v[188:189]
	v_pk_add_f32 v[62:63], v[62:63], v[194:195]
	v_pk_add_f32 v[60:61], v[60:61], v[192:193]
	v_pk_add_f32 v[62:63], v[62:63], v[198:199]
	v_pk_add_f32 v[60:61], v[60:61], v[196:197]
	v_pk_add_f32 v[62:63], v[62:63], v[202:203]
	v_pk_add_f32 v[60:61], v[60:61], v[200:201]
	v_pk_add_f32 v[62:63], v[62:63], v[206:207]
	v_pk_add_f32 v[60:61], v[60:61], v[204:205]
	v_pk_mul_f32 v[214:215], v[214:215], 0.5 op_sel_hi:[1,0]
	v_pk_mul_f32 v[212:213], v[212:213], 0.5 op_sel_hi:[1,0]
	v_pk_fma_f32 v[82:83], v[62:63], v[214:215], v[210:211]
	v_pk_fma_f32 v[80:81], v[60:61], v[212:213], v[208:209]
	v_mul_f32_e32 v67, v83, v83
	v_mul_f32_e32 v66, v81, v81
	v_fmac_f32_e32 v66, v80, v80
	v_fmac_f32_e32 v67, v82, v82
	global_store_dwordx4 v[54:55], v[80:83], off offset:3072
	v_add_f32_e32 v66, v66, v67
	v_add_f32_e32 v7, v7, v66
	v_pk_add_f32 v[222:223], v[222:223], 1.0 op_sel_hi:[1,0]
	v_pk_add_f32 v[220:221], v[220:221], 1.0 op_sel_hi:[1,0]
	v_pk_mul_f32 v[218:219], v[218:219], v[222:223]
	v_pk_mul_f32 v[216:217], v[216:217], v[220:221]
	v_pk_mul_f32 v[86:87], v[82:83], v[218:219]
	v_pk_mul_f32 v[84:85], v[80:81], v[216:217]
	s_nop 0
	v_cvt_pk_bf16_f32 v84, v84, v85
	v_cvt_pk_bf16_f32 v85, v86, v87
	global_store_dwordx2 v[58:59], v[84:85], off offset:1536
	ds_bpermute_b32 v2, v1, v7
	s_waitcnt lgkmcnt(0)
	v_add_f32_e32 v2, v7, v2
	ds_bpermute_b32 v3, v68, v2
	s_waitcnt lgkmcnt(0)
	v_add_f32_e32 v2, v2, v3
	ds_bpermute_b32 v3, v69, v2
	s_waitcnt lgkmcnt(0)
	v_add_f32_e32 v2, v2, v3
	ds_bpermute_b32 v3, v70, v2
	s_waitcnt lgkmcnt(0)
	v_add_f32_e32 v2, v2, v3
	ds_bpermute_b32 v3, v71, v2
	s_waitcnt lgkmcnt(0)
	v_add_f32_e32 v2, v2, v3
	ds_bpermute_b32 v3, v72, v2
	s_and_saveexec_b64 s[8:9], s[0:1]
	s_cbranch_execz .LBB0_471
	s_waitcnt lgkmcnt(0)
	v_add_f32_e32 v2, v2, v3
	global_store_dword v[30:31], v2, off
	s_branch .LBB0_471

.LBB0_1417:
	s_or_b64 exec, exec, s[0:1]
	v_readlane_b32 s0, v254, 28
	s_mul_i32 s33, s0, 3
	v_readlane_b32 s0, v254, 30
	v_readlane_b32 s1, v254, 31
	s_add_i32 s33, s33, 2
	s_and_b64 vcc, exec, s[0:1]
	s_movk_i32 s10, 0x100
	s_waitcnt lgkmcnt(0)
	s_barrier
	s_cbranch_vccnz .LBB0_1476
	s_cmp_lg_u32 s57, -1
	s_cselect_b32 s0, s57, 0
	s_cselect_b32 s1, s55, 0
	s_cmp_lg_u32 s58, -1
	v_mov_b64_e32 v[4:5], s[0:1]
	s_cselect_b32 s0, s58, 0
	s_cselect_b32 s1, s55, 0
	v_mov_b64_e32 v[6:7], s[0:1]
	ds_read_b32 v1, v4
	s_waitcnt vmcnt(0) lgkmcnt(0)
	ds_read_b32 v2, v6
	s_waitcnt vmcnt(0) lgkmcnt(0)
	s_cmp_lg_u32 s50, -1
	s_cselect_b32 s0, s50, 0
	s_cselect_b32 s1, s55, 0
	v_mov_b32_e32 v3, s1
	s_cmp_lg_u32 s51, -1
	s_cselect_b32 s1, s55, 0
	v_readlane_b32 s4, v253, 6
	s_waitcnt lgkmcnt(0)
	v_readfirstlane_b32 s6, v1
	v_readfirstlane_b32 s7, v2
	v_mov_b32_e32 v2, s0
	ds_read_b32 v1, v2
	s_waitcnt vmcnt(0) lgkmcnt(0)
	s_cselect_b32 s0, s51, 0
	v_mov_b32_e32 v2, s0
	v_mov_b32_e32 v3, s1
	ds_read_b32 v2, v2
	s_waitcnt vmcnt(0) lgkmcnt(0)
	v_readfirstlane_b32 s0, v1
	v_mov_b32_e32 v1, v224
	ds_read_b32 v3, v4
	s_waitcnt vmcnt(0) lgkmcnt(0)
	ds_read_b32 v4, v6
	s_waitcnt vmcnt(0) lgkmcnt(0)
	v_readfirstlane_b32 s1, v2
	v_ashrrev_i32_e32 v2, 6, v1
	v_mul_lo_u32 v2, v2, s76
	v_add_u32_e32 v2, s75, v2
	s_movk_i32 s4, 0x400
	v_cmp_gt_i32_e32 vcc, s4, v2
	s_waitcnt lgkmcnt(0)
	v_readfirstlane_b32 s8, v3
	v_readfirstlane_b32 s9, v4
	s_and_saveexec_b64 s[4:5], vcc
	s_cbranch_execz .LBB0_1423
	v_and_b32_e32 v3, 63, v1
	v_and_b32_e32 v1, 64, v230
	v_add_u32_e32 v4, 64, v1
	v_xor_b32_e32 v1, 1, v230
	v_cmp_lt_i32_e32 vcc, v1, v4
	v_xor_b32_e32 v5, 2, v230
	v_readlane_b32 s10, v254, 36
	v_cndmask_b32_e32 v1, v230, v1, vcc
	v_cmp_lt_i32_e32 vcc, v5, v4
	v_readlane_b32 s11, v254, 37
	s_lshl_b64 s[10:11], s[10:11], 2
	v_cndmask_b32_e32 v5, v230, v5, vcc
	v_lshlrev_b32_e32 v46, 2, v5
	v_xor_b32_e32 v5, 4, v230
	v_cmp_lt_i32_e32 vcc, v5, v4
	s_add_u32 s10, s0, s10
	s_addc_u32 s11, s1, s11
	v_cndmask_b32_e32 v5, v230, v5, vcc
	v_lshlrev_b32_e32 v47, 2, v5
	v_xor_b32_e32 v5, 8, v230
	v_cmp_lt_i32_e32 vcc, v5, v4
	s_add_u32 s0, s8, s53
	s_addc_u32 s1, s9, 0
	v_cndmask_b32_e32 v5, v230, v5, vcc
	v_lshlrev_b32_e32 v48, 2, v5
	v_xor_b32_e32 v5, 16, v230
	v_cmp_lt_i32_e32 vcc, v5, v4
	s_add_u32 s12, s0, 0x24000
	s_addc_u32 s13, s1, 0
	v_cndmask_b32_e32 v5, v230, v5, vcc
	v_lshlrev_b32_e32 v49, 2, v5
	v_xor_b32_e32 v5, 32, v230
	v_cmp_lt_i32_e32 vcc, v5, v4
	s_add_u32 s0, s8, s52
	v_lshlrev_b32_e32 v24, 3, v3
	v_cndmask_b32_e32 v4, v230, v5, vcc
	v_lshlrev_b32_e32 v50, 2, v4
	v_lshlrev_b32_e32 v4, 4, v3
	v_mov_b32_e32 v5, v0
	v_mov_b32_e32 v25, v0
	s_addc_u32 s1, s9, 0
	v_lshl_add_u64 v[8:9], s[10:11], 0, v[4:5]
	v_lshl_add_u64 v[24:25], s[8:9], 0, v[24:25]
	s_mov_b64 s[10:11], 0x5a00000
	s_add_u32 s14, s0, 0x24000
	v_lshl_add_u64 v[24:25], v[24:25], 0, s[10:11]
	v_readlane_b32 s10, v254, 28
	s_addc_u32 s15, s1, 0
	s_mul_hi_u32 s11, s10, 0x33000
	v_readlane_b32 s10, v254, 26
	s_add_u32 s10, s8, s10
	v_cmp_eq_u32_e64 s[0:1], 0, v3
	v_ashrrev_i32_e32 v3, 31, v2
	s_addc_u32 s11, s9, s11
	v_or_b32_e32 v14, 0x400, v4
	v_mov_b32_e32 v15, v0
	v_or_b32_e32 v18, 0x800, v4
	v_mov_b32_e32 v19, v0
	v_or_b32_e32 v22, 0xc00, v4
	v_mov_b32_e32 v23, v0
	v_lshl_add_u64 v[26:27], v[2:3], 2, s[10:11]
	s_mov_b64 s[10:11], 0x1b2000
	v_lshlrev_b64 v[30:31], 12, v[2:3]
	v_lshlrev_b32_e32 v1, 2, v1
	v_lshl_add_u64 v[6:7], s[14:15], 0, v[4:5]
	v_lshl_add_u64 v[10:11], s[12:13], 0, v[4:5]
	v_lshl_add_u64 v[12:13], s[14:15], 0, v[14:15]
	v_lshl_add_u64 v[14:15], s[12:13], 0, v[14:15]
	v_lshl_add_u64 v[16:17], s[14:15], 0, v[18:19]
	v_lshl_add_u64 v[18:19], s[12:13], 0, v[18:19]
	v_lshl_add_u64 v[20:21], s[14:15], 0, v[22:23]
	v_lshl_add_u64 v[22:23], s[12:13], 0, v[22:23]
	v_lshl_add_u64 v[26:27], v[26:27], 0, s[10:11]
	v_lshl_add_u64 v[28:29], s[8:9], 0, v[30:31]
	v_lshl_add_u64 v[30:31], s[6:7], 0, v[30:31]
	s_mov_b64 s[6:7], 0
	s_branch .LBB0_1421

.LBB0_1421:
	s_waitcnt lgkmcnt(0)
	v_lshl_add_u64 v[52:53], v[28:29], 0, v[4:5]
	v_lshl_add_u64 v[56:57], v[30:31], 0, v[4:5]
	v_add_u32_e32 v64, 0x4000, v2
	v_ashrrev_i32_e32 v65, 31, v64
	v_lshlrev_b64 v[58:59], 11, v[64:65]
	v_lshl_add_u64 v[58:59], v[24:25], 0, v[58:59]
	s_mov_b32 s85, 0
	s_mov_b32 s84, 0x400000
	v_lshl_add_u64 v[54:55], v[52:53], 0, s[84:85]
	v_lshl_add_u64 v[56:57], v[56:57], 0, s[84:85]
	s_mov_b32 s84, 0xda00000
	v_lshl_add_u64 v[88:89], v[52:53], 0, s[84:85]
	s_add_u32 s84, s84, 0x400000
	v_lshl_add_u64 v[90:91], v[52:53], 0, s[84:85]
	s_add_u32 s84, s84, 0x400000
	v_lshl_add_u64 v[92:93], v[52:53], 0, s[84:85]
	s_add_u32 s84, s84, 0x400000
	v_lshl_add_u64 v[94:95], v[52:53], 0, s[84:85]
	global_load_dwordx4 v[110:113], v[88:89], off
	global_load_dwordx4 v[114:117], v[90:91], off
	global_load_dwordx4 v[118:121], v[92:93], off
	global_load_dwordx4 v[122:125], v[94:95], off
	global_load_dwordx4 v[126:129], v[56:57], off
	global_load_dwordx4 v[130:133], v[6:7], off
	global_load_dwordx4 v[134:137], v[8:9], off
	global_load_dwordx4 v[138:141], v[10:11], off
	global_load_dwordx4 v[142:145], v[88:89], off offset:1024
	global_load_dwordx4 v[148:151], v[90:91], off offset:1024
	global_load_dwordx4 v[152:155], v[92:93], off offset:1024
	global_load_dwordx4 v[156:159], v[94:95], off offset:1024
	global_load_dwordx4 v[160:163], v[56:57], off offset:1024
	global_load_dwordx4 v[164:167], v[6:7], off offset:1024
	global_load_dwordx4 v[168:171], v[8:9], off offset:1024
	global_load_dwordx4 v[172:175], v[10:11], off offset:1024
	s_waitcnt vmcnt(8)
	v_pk_add_f32 v[62:63], v[112:113], 0 op_sel_hi:[1,0]
	v_pk_add_f32 v[60:61], v[110:111], 0 op_sel_hi:[1,0]
	v_pk_add_f32 v[62:63], v[62:63], v[116:117]
	v_pk_add_f32 v[60:61], v[60:61], v[114:115]
	v_pk_add_f32 v[62:63], v[62:63], v[120:121]
	v_pk_add_f32 v[60:61], v[60:61], v[118:119]
	v_pk_add_f32 v[62:63], v[62:63], v[124:125]
	v_pk_add_f32 v[60:61], v[60:61], v[122:123]
	v_pk_fma_f32 v[82:83], v[62:63], v[132:133], v[128:129]
	v_pk_fma_f32 v[80:81], v[60:61], v[130:131], v[126:127]
	v_mul_f32_e32 v66, v83, v83
	v_mul_f32_e32 v3, v81, v81
	global_store_dwordx4 v[54:55], v[80:83], off
	v_fmac_f32_e32 v3, v80, v80
	v_fmac_f32_e32 v66, v82, v82
	v_add_f32_e32 v3, v3, v66
	v_pk_add_f32 v[140:141], v[140:141], 1.0 op_sel_hi:[1,0]
	v_pk_add_f32 v[138:139], v[138:139], 1.0 op_sel_hi:[1,0]
	v_pk_mul_f32 v[136:137], v[136:137], v[140:141]
	v_pk_mul_f32 v[134:135], v[134:135], v[138:139]
	v_pk_mul_f32 v[86:87], v[82:83], v[136:137]
	v_pk_mul_f32 v[84:85], v[80:81], v[134:135]
	s_nop 0
	v_cvt_pk_bf16_f32 v84, v84, v85
	v_cvt_pk_bf16_f32 v85, v86, v87
	global_store_dwordx2 v[58:59], v[84:85], off
	global_load_dwordx4 v[110:113], v[88:89], off offset:2048
	global_load_dwordx4 v[114:117], v[90:91], off offset:2048
	global_load_dwordx4 v[118:121], v[92:93], off offset:2048
	global_load_dwordx4 v[122:125], v[94:95], off offset:2048
	global_load_dwordx4 v[126:129], v[56:57], off offset:2048
	global_load_dwordx4 v[130:133], v[6:7], off offset:2048
	global_load_dwordx4 v[134:137], v[8:9], off offset:2048
	global_load_dwordx4 v[138:141], v[10:11], off offset:2048
	s_waitcnt vmcnt(10)
	v_pk_add_f32 v[62:63], v[144:145], 0 op_sel_hi:[1,0]
	v_pk_add_f32 v[60:61], v[142:143], 0 op_sel_hi:[1,0]
	v_pk_add_f32 v[62:63], v[62:63], v[150:151]
	v_pk_add_f32 v[60:61], v[60:61], v[148:149]
	v_pk_add_f32 v[62:63], v[62:63], v[154:155]
	v_pk_add_f32 v[60:61], v[60:61], v[152:153]
	v_pk_add_f32 v[62:63], v[62:63], v[158:159]
	v_pk_add_f32 v[60:61], v[60:61], v[156:157]
	v_pk_fma_f32 v[82:83], v[62:63], v[166:167], v[162:163]
	v_pk_fma_f32 v[80:81], v[60:61], v[164:165], v[160:161]
	v_mul_f32_e32 v67, v83, v83
	v_mul_f32_e32 v66, v81, v81
	v_fmac_f32_e32 v66, v80, v80
	v_fmac_f32_e32 v67, v82, v82
	global_store_dwordx4 v[54:55], v[80:83], off offset:1024
	v_add_f32_e32 v66, v66, v67
	v_add_f32_e32 v3, v3, v66
	v_pk_add_f32 v[174:175], v[174:175], 1.0 op_sel_hi:[1,0]
	v_pk_add_f32 v[172:173], v[172:173], 1.0 op_sel_hi:[1,0]
	v_pk_mul_f32 v[170:171], v[170:171], v[174:175]
	v_pk_mul_f32 v[168:169], v[168:169], v[172:173]
	v_pk_mul_f32 v[86:87], v[82:83], v[170:171]
	v_pk_mul_f32 v[84:85], v[80:81], v[168:169]
	s_nop 0
	v_cvt_pk_bf16_f32 v84, v84, v85
	v_cvt_pk_bf16_f32 v85, v86, v87
	global_store_dwordx2 v[58:59], v[84:85], off offset:512
	global_load_dwordx4 v[142:145], v[88:89], off offset:3072
	global_load_dwordx4 v[148:151], v[90:91], off offset:3072
	global_load_dwordx4 v[152:155], v[92:93], off offset:3072
	global_load_dwordx4 v[156:159], v[94:95], off offset:3072
	global_load_dwordx4 v[160:163], v[56:57], off offset:3072
	global_load_dwordx4 v[164:167], v[6:7], off offset:3072
	global_load_dwordx4 v[168:171], v[8:9], off offset:3072
	global_load_dwordx4 v[172:175], v[10:11], off offset:3072
	s_waitcnt vmcnt(10)
	v_pk_add_f32 v[62:63], v[112:113], 0 op_sel_hi:[1,0]
	v_pk_add_f32 v[60:61], v[110:111], 0 op_sel_hi:[1,0]
	v_pk_add_f32 v[62:63], v[62:63], v[116:117]
	v_pk_add_f32 v[60:61], v[60:61], v[114:115]
	v_pk_add_f32 v[62:63], v[62:63], v[120:121]
	v_pk_add_f32 v[60:61], v[60:61], v[118:119]
	v_pk_add_f32 v[62:63], v[62:63], v[124:125]
	v_pk_add_f32 v[60:61], v[60:61], v[122:123]
	v_pk_fma_f32 v[82:83], v[62:63], v[132:133], v[128:129]
	v_pk_fma_f32 v[80:81], v[60:61], v[130:131], v[126:127]
	v_mul_f32_e32 v67, v83, v83
	v_mul_f32_e32 v66, v81, v81
	v_fmac_f32_e32 v66, v80, v80
	v_fmac_f32_e32 v67, v82, v82
	global_store_dwordx4 v[54:55], v[80:83], off offset:2048
	v_add_f32_e32 v66, v66, v67
	v_add_f32_e32 v3, v3, v66
	v_pk_add_f32 v[140:141], v[140:141], 1.0 op_sel_hi:[1,0]
	v_pk_add_f32 v[138:139], v[138:139], 1.0 op_sel_hi:[1,0]
	v_pk_mul_f32 v[136:137], v[136:137], v[140:141]
	v_pk_mul_f32 v[134:135], v[134:135], v[138:139]
	v_pk_mul_f32 v[86:87], v[82:83], v[136:137]
	v_pk_mul_f32 v[84:85], v[80:81], v[134:135]
	s_nop 0
	v_cvt_pk_bf16_f32 v84, v84, v85
	v_cvt_pk_bf16_f32 v85, v86, v87
	global_store_dwordx2 v[58:59], v[84:85], off offset:1024
	s_waitcnt vmcnt(2)
	v_pk_add_f32 v[62:63], v[144:145], 0 op_sel_hi:[1,0]
	v_pk_add_f32 v[60:61], v[142:143], 0 op_sel_hi:[1,0]
	v_pk_add_f32 v[62:63], v[62:63], v[150:151]
	v_pk_add_f32 v[60:61], v[60:61], v[148:149]
	v_pk_add_f32 v[62:63], v[62:63], v[154:155]
	v_pk_add_f32 v[60:61], v[60:61], v[152:153]
	v_pk_add_f32 v[62:63], v[62:63], v[158:159]
	v_pk_add_f32 v[60:61], v[60:61], v[156:157]
	v_pk_fma_f32 v[82:83], v[62:63], v[166:167], v[162:163]
	v_pk_fma_f32 v[80:81], v[60:61], v[164:165], v[160:161]
	v_mul_f32_e32 v67, v83, v83
	v_mul_f32_e32 v66, v81, v81
	v_fmac_f32_e32 v66, v80, v80
	v_fmac_f32_e32 v67, v82, v82
	global_store_dwordx4 v[54:55], v[80:83], off offset:3072
	v_add_f32_e32 v66, v66, v67
	v_add_f32_e32 v3, v3, v66
	v_pk_add_f32 v[174:175], v[174:175], 1.0 op_sel_hi:[1,0]
	v_pk_add_f32 v[172:173], v[172:173], 1.0 op_sel_hi:[1,0]
	v_pk_mul_f32 v[170:171], v[170:171], v[174:175]
	v_pk_mul_f32 v[168:169], v[168:169], v[172:173]
	v_pk_mul_f32 v[86:87], v[82:83], v[170:171]
	v_pk_mul_f32 v[84:85], v[80:81], v[168:169]
	s_nop 0
	v_cvt_pk_bf16_f32 v84, v84, v85
	v_cvt_pk_bf16_f32 v85, v86, v87
	global_store_dwordx2 v[58:59], v[84:85], off offset:1536
	ds_bpermute_b32 v32, v1, v3
	s_waitcnt lgkmcnt(0)
	v_add_f32_e32 v3, v3, v32
	ds_bpermute_b32 v32, v46, v3
	s_waitcnt lgkmcnt(0)
	v_add_f32_e32 v3, v3, v32
	ds_bpermute_b32 v32, v47, v3
	s_waitcnt lgkmcnt(0)
	v_add_f32_e32 v3, v3, v32
	ds_bpermute_b32 v32, v48, v3
	s_waitcnt lgkmcnt(0)
	v_add_f32_e32 v3, v3, v32
	ds_bpermute_b32 v32, v49, v3
	s_waitcnt lgkmcnt(0)
	v_add_f32_e32 v3, v3, v32
	ds_bpermute_b32 v32, v50, v3
	s_and_saveexec_b64 s[8:9], s[0:1]
	s_cbranch_execz .LBB0_1420
	s_waitcnt lgkmcnt(0)
	v_add_f32_e32 v3, v3, v32
	global_store_dword v[26:27], v3, off
	s_branch .LBB0_1420

.LBB0_1727:
	s_waitcnt lgkmcnt(0)
	v_lshl_add_u64 v[52:53], v[38:39], 0, v[8:9]
	v_lshl_add_u64 v[56:57], v[40:41], 0, v[8:9]
	v_add_u32_e32 v64, 0x4000, v6
	v_ashrrev_i32_e32 v65, 31, v64
	v_lshlrev_b64 v[58:59], 11, v[64:65]
	v_lshl_add_u64 v[58:59], v[34:35], 0, v[58:59]
	s_mov_b32 s85, 0
	s_mov_b32 s84, 0x400000
	v_lshl_add_u64 v[54:55], v[52:53], 0, s[84:85]
	v_lshl_add_u64 v[56:57], v[56:57], 0, s[84:85]
	s_mov_b32 s84, 0xda00000
	v_lshl_add_u64 v[88:89], v[52:53], 0, s[84:85]
	s_add_u32 s84, s84, 0x400000
	v_lshl_add_u64 v[90:91], v[52:53], 0, s[84:85]
	s_add_u32 s84, s84, 0x400000
	v_lshl_add_u64 v[92:93], v[52:53], 0, s[84:85]
	s_add_u32 s84, s84, 0x400000
	v_lshl_add_u64 v[94:95], v[52:53], 0, s[84:85]
	s_add_u32 s84, s84, 0x400000
	v_lshl_add_u64 v[96:97], v[52:53], 0, s[84:85]
	s_add_u32 s84, s84, 0x400000
	v_lshl_add_u64 v[98:99], v[52:53], 0, s[84:85]
	s_add_u32 s84, s84, 0x400000
	v_lshl_add_u64 v[100:101], v[52:53], 0, s[84:85]
	s_add_u32 s84, s84, 0x400000
	v_lshl_add_u64 v[102:103], v[52:53], 0, s[84:85]
	s_add_u32 s84, s84, 0x400000
	v_lshl_add_u64 v[104:105], v[52:53], 0, s[84:85]
	s_add_u32 s84, s84, 0x400000
	v_lshl_add_u64 v[106:107], v[52:53], 0, s[84:85]
	s_add_u32 s84, s84, 0x400000
	v_lshl_add_u64 v[108:109], v[52:53], 0, s[84:85]
	global_load_dwordx4 v[42:45], v[88:89], off
	global_load_dwordx4 v[46:49], v[90:91], off
	global_load_dwordx4 v[110:113], v[92:93], off
	global_load_dwordx4 v[114:117], v[94:95], off
	global_load_dwordx4 v[118:121], v[96:97], off
	global_load_dwordx4 v[122:125], v[98:99], off
	global_load_dwordx4 v[126:129], v[100:101], off
	global_load_dwordx4 v[130:133], v[102:103], off
	global_load_dwordx4 v[134:137], v[104:105], off
	global_load_dwordx4 v[138:141], v[106:107], off
	global_load_dwordx4 v[142:145], v[108:109], off
	global_load_dwordx4 v[148:151], v[56:57], off
	global_load_dwordx4 v[152:155], v[10:11], off
	global_load_dwordx4 v[156:159], v[12:13], off
	global_load_dwordx4 v[160:163], v[14:15], off
	global_load_dwordx4 v[164:167], v[88:89], off offset:1024
	global_load_dwordx4 v[168:171], v[90:91], off offset:1024
	global_load_dwordx4 v[172:175], v[92:93], off offset:1024
	global_load_dwordx4 v[176:179], v[94:95], off offset:1024
	global_load_dwordx4 v[180:183], v[96:97], off offset:1024
	global_load_dwordx4 v[184:187], v[98:99], off offset:1024
	global_load_dwordx4 v[188:191], v[100:101], off offset:1024
	global_load_dwordx4 v[192:195], v[102:103], off offset:1024
	global_load_dwordx4 v[196:199], v[104:105], off offset:1024
	global_load_dwordx4 v[200:203], v[106:107], off offset:1024
	global_load_dwordx4 v[204:207], v[108:109], off offset:1024
	global_load_dwordx4 v[208:211], v[56:57], off offset:1024
	global_load_dwordx4 v[212:215], v[10:11], off offset:1024
	global_load_dwordx4 v[216:219], v[12:13], off offset:1024
	global_load_dwordx4 v[220:223], v[14:15], off offset:1024
	s_waitcnt vmcnt(15)
	v_pk_add_f32 v[62:63], v[44:45], 0 op_sel_hi:[1,0]
	v_pk_add_f32 v[60:61], v[42:43], 0 op_sel_hi:[1,0]
	v_pk_add_f32 v[62:63], v[62:63], v[48:49]
	v_pk_add_f32 v[60:61], v[60:61], v[46:47]
	v_pk_add_f32 v[62:63], v[62:63], v[112:113]
	v_pk_add_f32 v[60:61], v[60:61], v[110:111]
	v_pk_add_f32 v[62:63], v[62:63], v[116:117]
	v_pk_add_f32 v[60:61], v[60:61], v[114:115]
	v_pk_add_f32 v[62:63], v[62:63], v[120:121]
	v_pk_add_f32 v[60:61], v[60:61], v[118:119]
	v_pk_add_f32 v[62:63], v[62:63], v[124:125]
	v_pk_add_f32 v[60:61], v[60:61], v[122:123]
	v_pk_add_f32 v[62:63], v[62:63], v[128:129]
	v_pk_add_f32 v[60:61], v[60:61], v[126:127]
	v_pk_add_f32 v[62:63], v[62:63], v[132:133]
	v_pk_add_f32 v[60:61], v[60:61], v[130:131]
	v_pk_add_f32 v[62:63], v[62:63], v[136:137]
	v_pk_add_f32 v[60:61], v[60:61], v[134:135]
	v_pk_add_f32 v[62:63], v[62:63], v[140:141]
	v_pk_add_f32 v[60:61], v[60:61], v[138:139]
	v_pk_add_f32 v[62:63], v[62:63], v[144:145]
	v_pk_add_f32 v[60:61], v[60:61], v[142:143]
	v_pk_mul_f32 v[154:155], v[154:155], 0.5 op_sel_hi:[1,0]
	v_pk_mul_f32 v[152:153], v[152:153], 0.5 op_sel_hi:[1,0]
	v_pk_fma_f32 v[82:83], v[62:63], v[154:155], v[150:151]
	v_pk_fma_f32 v[80:81], v[60:61], v[152:153], v[148:149]
	v_mul_f32_e32 v66, v83, v83
	v_mul_f32_e32 v7, v81, v81
	global_store_dwordx4 v[54:55], v[80:83], off
	v_fmac_f32_e32 v7, v80, v80
	v_fmac_f32_e32 v66, v82, v82
	v_add_f32_e32 v7, v7, v66
	v_pk_add_f32 v[162:163], v[162:163], 1.0 op_sel_hi:[1,0]
	v_pk_add_f32 v[160:161], v[160:161], 1.0 op_sel_hi:[1,0]
	v_pk_mul_f32 v[158:159], v[158:159], v[162:163]
	v_pk_mul_f32 v[156:157], v[156:157], v[160:161]
	v_pk_mul_f32 v[86:87], v[82:83], v[158:159]
	v_pk_mul_f32 v[84:85], v[80:81], v[156:157]
	s_nop 0
	v_cvt_pk_bf16_f32 v84, v84, v85
	v_cvt_pk_bf16_f32 v85, v86, v87
	global_store_dwordx2 v[58:59], v[84:85], off
	global_load_dwordx4 v[42:45], v[88:89], off offset:2048
	global_load_dwordx4 v[46:49], v[90:91], off offset:2048
	global_load_dwordx4 v[110:113], v[92:93], off offset:2048
	global_load_dwordx4 v[114:117], v[94:95], off offset:2048
	global_load_dwordx4 v[118:121], v[96:97], off offset:2048
	global_load_dwordx4 v[122:125], v[98:99], off offset:2048
	global_load_dwordx4 v[126:129], v[100:101], off offset:2048
	global_load_dwordx4 v[130:133], v[102:103], off offset:2048
	global_load_dwordx4 v[134:137], v[104:105], off offset:2048
	global_load_dwordx4 v[138:141], v[106:107], off offset:2048
	global_load_dwordx4 v[142:145], v[108:109], off offset:2048
	global_load_dwordx4 v[148:151], v[56:57], off offset:2048
	global_load_dwordx4 v[152:155], v[10:11], off offset:2048
	global_load_dwordx4 v[156:159], v[12:13], off offset:2048
	global_load_dwordx4 v[160:163], v[14:15], off offset:2048
	s_waitcnt vmcnt(17)
	v_pk_add_f32 v[62:63], v[166:167], 0 op_sel_hi:[1,0]
	v_pk_add_f32 v[60:61], v[164:165], 0 op_sel_hi:[1,0]
	v_pk_add_f32 v[62:63], v[62:63], v[170:171]
	v_pk_add_f32 v[60:61], v[60:61], v[168:169]
	v_pk_add_f32 v[62:63], v[62:63], v[174:175]
	v_pk_add_f32 v[60:61], v[60:61], v[172:173]
	v_pk_add_f32 v[62:63], v[62:63], v[178:179]
	v_pk_add_f32 v[60:61], v[60:61], v[176:177]
	v_pk_add_f32 v[62:63], v[62:63], v[182:183]
	v_pk_add_f32 v[60:61], v[60:61], v[180:181]
	v_pk_add_f32 v[62:63], v[62:63], v[186:187]
	v_pk_add_f32 v[60:61], v[60:61], v[184:185]
	v_pk_add_f32 v[62:63], v[62:63], v[190:191]
	v_pk_add_f32 v[60:61], v[60:61], v[188:189]
	v_pk_add_f32 v[62:63], v[62:63], v[194:195]
	v_pk_add_f32 v[60:61], v[60:61], v[192:193]
	v_pk_add_f32 v[62:63], v[62:63], v[198:199]
	v_pk_add_f32 v[60:61], v[60:61], v[196:197]
	v_pk_add_f32 v[62:63], v[62:63], v[202:203]
	v_pk_add_f32 v[60:61], v[60:61], v[200:201]
	v_pk_add_f32 v[62:63], v[62:63], v[206:207]
	v_pk_add_f32 v[60:61], v[60:61], v[204:205]
	v_pk_mul_f32 v[214:215], v[214:215], 0.5 op_sel_hi:[1,0]
	v_pk_mul_f32 v[212:213], v[212:213], 0.5 op_sel_hi:[1,0]
	v_pk_fma_f32 v[82:83], v[62:63], v[214:215], v[210:211]
	v_pk_fma_f32 v[80:81], v[60:61], v[212:213], v[208:209]
	v_mul_f32_e32 v67, v83, v83
	v_mul_f32_e32 v66, v81, v81
	v_fmac_f32_e32 v66, v80, v80
	v_fmac_f32_e32 v67, v82, v82
	global_store_dwordx4 v[54:55], v[80:83], off offset:1024
	v_add_f32_e32 v66, v66, v67
	v_add_f32_e32 v7, v7, v66
	v_pk_add_f32 v[222:223], v[222:223], 1.0 op_sel_hi:[1,0]
	v_pk_add_f32 v[220:221], v[220:221], 1.0 op_sel_hi:[1,0]
	v_pk_mul_f32 v[218:219], v[218:219], v[222:223]
	v_pk_mul_f32 v[216:217], v[216:217], v[220:221]
	v_pk_mul_f32 v[86:87], v[82:83], v[218:219]
	v_pk_mul_f32 v[84:85], v[80:81], v[216:217]
	s_nop 0
	v_cvt_pk_bf16_f32 v84, v84, v85
	v_cvt_pk_bf16_f32 v85, v86, v87
	global_store_dwordx2 v[58:59], v[84:85], off offset:512
	global_load_dwordx4 v[164:167], v[88:89], off offset:3072
	global_load_dwordx4 v[168:171], v[90:91], off offset:3072
	global_load_dwordx4 v[172:175], v[92:93], off offset:3072
	global_load_dwordx4 v[176:179], v[94:95], off offset:3072
	global_load_dwordx4 v[180:183], v[96:97], off offset:3072
	global_load_dwordx4 v[184:187], v[98:99], off offset:3072
	global_load_dwordx4 v[188:191], v[100:101], off offset:3072
	global_load_dwordx4 v[192:195], v[102:103], off offset:3072
	global_load_dwordx4 v[196:199], v[104:105], off offset:3072
	global_load_dwordx4 v[200:203], v[106:107], off offset:3072
	global_load_dwordx4 v[204:207], v[108:109], off offset:3072
	global_load_dwordx4 v[208:211], v[56:57], off offset:3072
	global_load_dwordx4 v[212:215], v[10:11], off offset:3072
	global_load_dwordx4 v[216:219], v[12:13], off offset:3072
	global_load_dwordx4 v[220:223], v[14:15], off offset:3072
	s_waitcnt vmcnt(17)
	v_pk_add_f32 v[62:63], v[44:45], 0 op_sel_hi:[1,0]
	v_pk_add_f32 v[60:61], v[42:43], 0 op_sel_hi:[1,0]
	v_pk_add_f32 v[62:63], v[62:63], v[48:49]
	v_pk_add_f32 v[60:61], v[60:61], v[46:47]
	v_pk_add_f32 v[62:63], v[62:63], v[112:113]
	v_pk_add_f32 v[60:61], v[60:61], v[110:111]
	v_pk_add_f32 v[62:63], v[62:63], v[116:117]
	v_pk_add_f32 v[60:61], v[60:61], v[114:115]
	v_pk_add_f32 v[62:63], v[62:63], v[120:121]
	v_pk_add_f32 v[60:61], v[60:61], v[118:119]
	v_pk_add_f32 v[62:63], v[62:63], v[124:125]
	v_pk_add_f32 v[60:61], v[60:61], v[122:123]
	v_pk_add_f32 v[62:63], v[62:63], v[128:129]
	v_pk_add_f32 v[60:61], v[60:61], v[126:127]
	v_pk_add_f32 v[62:63], v[62:63], v[132:133]
	v_pk_add_f32 v[60:61], v[60:61], v[130:131]
	v_pk_add_f32 v[62:63], v[62:63], v[136:137]
	v_pk_add_f32 v[60:61], v[60:61], v[134:135]
	v_pk_add_f32 v[62:63], v[62:63], v[140:141]
	v_pk_add_f32 v[60:61], v[60:61], v[138:139]
	v_pk_add_f32 v[62:63], v[62:63], v[144:145]
	v_pk_add_f32 v[60:61], v[60:61], v[142:143]
	v_pk_mul_f32 v[154:155], v[154:155], 0.5 op_sel_hi:[1,0]
	v_pk_mul_f32 v[152:153], v[152:153], 0.5 op_sel_hi:[1,0]
	v_pk_fma_f32 v[82:83], v[62:63], v[154:155], v[150:151]
	v_pk_fma_f32 v[80:81], v[60:61], v[152:153], v[148:149]
	v_mul_f32_e32 v67, v83, v83
	v_mul_f32_e32 v66, v81, v81
	v_fmac_f32_e32 v66, v80, v80
	v_fmac_f32_e32 v67, v82, v82
	global_store_dwordx4 v[54:55], v[80:83], off offset:2048
	v_add_f32_e32 v66, v66, v67
	v_add_f32_e32 v7, v7, v66
	v_pk_add_f32 v[162:163], v[162:163], 1.0 op_sel_hi:[1,0]
	v_pk_add_f32 v[160:161], v[160:161], 1.0 op_sel_hi:[1,0]
	v_pk_mul_f32 v[158:159], v[158:159], v[162:163]
	v_pk_mul_f32 v[156:157], v[156:157], v[160:161]
	v_pk_mul_f32 v[86:87], v[82:83], v[158:159]
	v_pk_mul_f32 v[84:85], v[80:81], v[156:157]
	s_nop 0
	v_cvt_pk_bf16_f32 v84, v84, v85
	v_cvt_pk_bf16_f32 v85, v86, v87
	global_store_dwordx2 v[58:59], v[84:85], off offset:1024
	s_waitcnt vmcnt(2)
	v_pk_add_f32 v[62:63], v[166:167], 0 op_sel_hi:[1,0]
	v_pk_add_f32 v[60:61], v[164:165], 0 op_sel_hi:[1,0]
	v_pk_add_f32 v[62:63], v[62:63], v[170:171]
	v_pk_add_f32 v[60:61], v[60:61], v[168:169]
	v_pk_add_f32 v[62:63], v[62:63], v[174:175]
	v_pk_add_f32 v[60:61], v[60:61], v[172:173]
	v_pk_add_f32 v[62:63], v[62:63], v[178:179]
	v_pk_add_f32 v[60:61], v[60:61], v[176:177]
	v_pk_add_f32 v[62:63], v[62:63], v[182:183]
	v_pk_add_f32 v[60:61], v[60:61], v[180:181]
	v_pk_add_f32 v[62:63], v[62:63], v[186:187]
	v_pk_add_f32 v[60:61], v[60:61], v[184:185]
	v_pk_add_f32 v[62:63], v[62:63], v[190:191]
	v_pk_add_f32 v[60:61], v[60:61], v[188:189]
	v_pk_add_f32 v[62:63], v[62:63], v[194:195]
	v_pk_add_f32 v[60:61], v[60:61], v[192:193]
	v_pk_add_f32 v[62:63], v[62:63], v[198:199]
	v_pk_add_f32 v[60:61], v[60:61], v[196:197]
	v_pk_add_f32 v[62:63], v[62:63], v[202:203]
	v_pk_add_f32 v[60:61], v[60:61], v[200:201]
	v_pk_add_f32 v[62:63], v[62:63], v[206:207]
	v_pk_add_f32 v[60:61], v[60:61], v[204:205]
	v_pk_mul_f32 v[214:215], v[214:215], 0.5 op_sel_hi:[1,0]
	v_pk_mul_f32 v[212:213], v[212:213], 0.5 op_sel_hi:[1,0]
	v_pk_fma_f32 v[82:83], v[62:63], v[214:215], v[210:211]
	v_pk_fma_f32 v[80:81], v[60:61], v[212:213], v[208:209]
	v_mul_f32_e32 v67, v83, v83
	v_mul_f32_e32 v66, v81, v81
	v_fmac_f32_e32 v66, v80, v80
	v_fmac_f32_e32 v67, v82, v82
	global_store_dwordx4 v[54:55], v[80:83], off offset:3072
	v_add_f32_e32 v66, v66, v67
	v_add_f32_e32 v7, v7, v66
	v_pk_add_f32 v[222:223], v[222:223], 1.0 op_sel_hi:[1,0]
	v_pk_add_f32 v[220:221], v[220:221], 1.0 op_sel_hi:[1,0]
	v_pk_mul_f32 v[218:219], v[218:219], v[222:223]
	v_pk_mul_f32 v[216:217], v[216:217], v[220:221]
	v_pk_mul_f32 v[86:87], v[82:83], v[218:219]
	v_pk_mul_f32 v[84:85], v[80:81], v[216:217]
	s_nop 0
	v_cvt_pk_bf16_f32 v84, v84, v85
	v_cvt_pk_bf16_f32 v85, v86, v87
	global_store_dwordx2 v[58:59], v[84:85], off offset:1536
	ds_bpermute_b32 v2, v1, v7
	s_waitcnt lgkmcnt(0)
	v_add_f32_e32 v2, v7, v2
	ds_bpermute_b32 v3, v74, v2
	s_waitcnt lgkmcnt(0)
	v_add_f32_e32 v2, v2, v3
	ds_bpermute_b32 v3, v75, v2
	s_waitcnt lgkmcnt(0)
	v_add_f32_e32 v2, v2, v3
	ds_bpermute_b32 v3, v76, v2
	s_waitcnt lgkmcnt(0)
	v_add_f32_e32 v2, v2, v3
	ds_bpermute_b32 v3, v77, v2
	s_waitcnt lgkmcnt(0)
	v_add_f32_e32 v2, v2, v3
	ds_bpermute_b32 v3, v78, v2
	s_and_saveexec_b64 s[8:9], s[0:1]
	s_cbranch_execz .LBB0_1726
	s_waitcnt lgkmcnt(0)
	v_add_f32_e32 v2, v2, v3
	global_store_dword v[36:37], v2, off
	s_branch .LBB0_1726
